# residual epilogue: the 16 residual-stream loads issued in two batches of 8 instead of one at a time
# speedup vs baseline: 1.0013x; 1.0013x over previous
.LBB0_693:
	v_lshl_add_u32 v166, s9, 8, v163
	v_ashrrev_i32_e32 v167, 31, v166
	v_lshlrev_b64 v[168:169], 10, v[166:167]
	v_lshl_add_u64 v[170:171], v[168:169], 0, v[164:165]
	v_lshl_add_u64 v[172:173], v[170:171], 1, s[28:29]
	v_mov_b32_e32 v198, v172
	v_mov_b32_e32 v199, v173
	v_mov_b32_e32 v182, v172
	v_mov_b32_e32 v183, v173
	s_mov_b64 s[42:43], 0x8000
	global_load_dwordx4 v[184:187], v[182:183], off
	global_load_dwordx4 v[212:215], v[182:183], off offset:256
	v_lshl_add_u64 v[182:183], v[182:183], 0, s[42:43]
	global_load_dwordx4 v[216:219], v[182:183], off
	global_load_dwordx4 v[220:223], v[182:183], off offset:256
	v_lshl_add_u64 v[182:183], v[182:183], 0, s[42:43]
	global_load_dwordx4 v[224:227], v[182:183], off
	global_load_dwordx4 v[228:231], v[182:183], off offset:256
	v_lshl_add_u64 v[182:183], v[182:183], 0, s[42:43]
	global_load_dwordx4 v[232:235], v[182:183], off
	global_load_dwordx4 v[236:239], v[182:183], off offset:256
	s_andn2_b64 vcc, exec, s[50:51]
	s_waitcnt vmcnt(7)
	v_mov_b32_e32 v178, v184
	v_mov_b32_e32 v179, v185
	v_mov_b32_e32 v180, v186
	v_mov_b32_e32 v181, v187
	v_lshlrev_b32_e32 v168, 16, v178
	v_and_b32_e32 v169, 0xffff0000, v178
	v_lshlrev_b32_e32 v178, 16, v179
	v_and_b32_e32 v179, 0xffff0000, v179
	v_pk_fma_f32 v[142:143], v[142:143], v[50:51], v[168:169]
	v_lshlrev_b32_e32 v168, 16, v180
	v_and_b32_e32 v169, 0xffff0000, v180
	v_pk_fma_f32 v[144:145], v[144:145], v[52:53], v[178:179]
	v_lshlrev_b32_e32 v178, 16, v181
	v_and_b32_e32 v179, 0xffff0000, v181
	v_pk_fma_f32 v[138:139], v[138:139], v[54:55], v[168:169]
	v_cndmask_b32_e64 v168, 0, 1, s[50:51]
	v_pk_fma_f32 v[140:141], v[140:141], v[56:57], v[178:179]
	v_cmp_ne_u32_e64 s[38:39], 1, v168
	v_lshl_add_u64 v[168:169], v[170:171], 2, s[16:17]
	s_cbranch_vccnz .LBB0_776
	global_store_dwordx4 v[168:169], v[142:145], off
	global_store_dwordx4 v[168:169], v[138:141], off offset:16
	v_mov_b32_e32 v178, 0
	s_cbranch_execnz .LBB0_696

.LBB0_696:
	v_lshlrev_b64 v[138:139], 1, v[170:171]
	v_or_b32_e32 v138, 0x100, v138
	v_lshl_add_u64 v[138:139], s[28:29], 0, v[138:139]
	s_and_b64 vcc, exec, s[38:39]
	s_waitcnt vmcnt(7)
	v_mov_b32_e32 v140, v212
	v_mov_b32_e32 v141, v213
	v_mov_b32_e32 v142, v214
	v_mov_b32_e32 v143, v215
	v_lshlrev_b32_e32 v144, 16, v140
	v_and_b32_e32 v145, 0xffff0000, v140
	v_lshlrev_b32_e32 v140, 16, v141
	v_and_b32_e32 v141, 0xffff0000, v141
	v_pk_fma_f32 v[136:137], v[136:137], v[40:41], v[140:141]
	v_lshlrev_b32_e32 v140, 16, v142
	v_and_b32_e32 v141, 0xffff0000, v142
	v_lshlrev_b32_e32 v142, 16, v143
	v_and_b32_e32 v143, 0xffff0000, v143
	v_pk_fma_f32 v[134:135], v[134:135], v[38:39], v[144:145]
	v_pk_fma_f32 v[132:133], v[132:133], v[48:49], v[142:143]
	v_pk_fma_f32 v[130:131], v[130:131], v[46:47], v[140:141]
	s_cbranch_vccnz .LBB0_777
	global_store_dwordx4 v[168:169], v[134:137], off offset:512
	global_store_dwordx4 v[168:169], v[130:133], off offset:528
	s_cbranch_execnz .LBB0_699

.LBB0_703:
	v_or_b32_e32 v130, 16, v166
	s_waitcnt lgkmcnt(0)
	v_ashrrev_i32_e32 v131, 31, v130
	v_lshlrev_b64 v[132:133], 10, v[130:131]
	v_lshl_add_u64 v[134:135], v[132:133], 0, v[164:165]
	v_lshl_add_u64 v[136:137], v[134:135], 1, s[28:29]
	s_and_b64 vcc, exec, s[38:39]
	s_waitcnt vmcnt(7)
	v_mov_b32_e32 v138, v216
	v_mov_b32_e32 v139, v217
	v_mov_b32_e32 v140, v218
	v_mov_b32_e32 v141, v219
	v_lshlrev_b32_e32 v132, 16, v138
	v_and_b32_e32 v133, 0xffff0000, v138
	v_lshlrev_b32_e32 v138, 16, v139
	v_and_b32_e32 v139, 0xffff0000, v139
	v_pk_fma_f32 v[128:129], v[128:129], v[52:53], v[138:139]
	v_pk_fma_f32 v[126:127], v[126:127], v[50:51], v[132:133]
	v_lshlrev_b32_e32 v132, 16, v140
	v_and_b32_e32 v133, 0xffff0000, v140
	v_lshlrev_b32_e32 v138, 16, v141
	v_and_b32_e32 v139, 0xffff0000, v141
	v_pk_fma_f32 v[124:125], v[124:125], v[56:57], v[138:139]
	v_pk_fma_f32 v[122:123], v[122:123], v[54:55], v[132:133]
	v_lshl_add_u64 v[132:133], v[134:135], 2, s[16:17]
	s_cbranch_vccnz .LBB0_778
	global_store_dwordx4 v[132:133], v[126:129], off
	global_store_dwordx4 v[132:133], v[122:125], off offset:16
	v_mov_b32_e32 v138, 0
	s_cbranch_execnz .LBB0_706

.LBB0_706:
	v_lshlrev_b64 v[122:123], 1, v[134:135]
	v_or_b32_e32 v122, 0x100, v122
	v_lshl_add_u64 v[122:123], s[28:29], 0, v[122:123]
	s_and_b64 vcc, exec, s[38:39]
	s_waitcnt vmcnt(7)
	v_mov_b32_e32 v124, v220
	v_mov_b32_e32 v125, v221
	v_mov_b32_e32 v126, v222
	v_mov_b32_e32 v127, v223
	v_lshlrev_b32_e32 v128, 16, v124
	v_and_b32_e32 v129, 0xffff0000, v124
	v_lshlrev_b32_e32 v124, 16, v125
	v_and_b32_e32 v125, 0xffff0000, v125
	v_pk_fma_f32 v[120:121], v[120:121], v[40:41], v[124:125]
	v_lshlrev_b32_e32 v124, 16, v126
	v_and_b32_e32 v125, 0xffff0000, v126
	v_lshlrev_b32_e32 v126, 16, v127
	v_and_b32_e32 v127, 0xffff0000, v127
	v_pk_fma_f32 v[118:119], v[118:119], v[38:39], v[128:129]
	v_pk_fma_f32 v[116:117], v[116:117], v[48:49], v[126:127]
	v_pk_fma_f32 v[114:115], v[114:115], v[46:47], v[124:125]
	s_cbranch_vccnz .LBB0_779
	global_store_dwordx4 v[132:133], v[118:121], off offset:512
	global_store_dwordx4 v[132:133], v[114:117], off offset:528
	s_cbranch_execnz .LBB0_709

.LBB0_713:
	v_or_b32_e32 v114, 32, v166
	s_waitcnt lgkmcnt(0)
	v_ashrrev_i32_e32 v115, 31, v114
	v_lshlrev_b64 v[116:117], 10, v[114:115]
	v_lshl_add_u64 v[118:119], v[116:117], 0, v[164:165]
	v_lshl_add_u64 v[120:121], v[118:119], 1, s[28:29]
	s_and_b64 vcc, exec, s[38:39]
	s_waitcnt vmcnt(7)
	v_mov_b32_e32 v122, v224
	v_mov_b32_e32 v123, v225
	v_mov_b32_e32 v124, v226
	v_mov_b32_e32 v125, v227
	v_lshlrev_b32_e32 v116, 16, v122
	v_and_b32_e32 v117, 0xffff0000, v122
	v_lshlrev_b32_e32 v122, 16, v123
	v_and_b32_e32 v123, 0xffff0000, v123
	v_pk_fma_f32 v[112:113], v[112:113], v[52:53], v[122:123]
	v_pk_fma_f32 v[110:111], v[110:111], v[50:51], v[116:117]
	v_lshlrev_b32_e32 v116, 16, v124
	v_and_b32_e32 v117, 0xffff0000, v124
	v_lshlrev_b32_e32 v122, 16, v125
	v_and_b32_e32 v123, 0xffff0000, v125
	v_pk_fma_f32 v[108:109], v[108:109], v[56:57], v[122:123]
	v_pk_fma_f32 v[106:107], v[106:107], v[54:55], v[116:117]
	v_lshl_add_u64 v[116:117], v[118:119], 2, s[16:17]
	s_cbranch_vccnz .LBB0_780
	global_store_dwordx4 v[116:117], v[110:113], off
	global_store_dwordx4 v[116:117], v[106:109], off offset:16
	v_mov_b32_e32 v122, 0
	s_cbranch_execnz .LBB0_716

.LBB0_716:
	v_lshlrev_b64 v[106:107], 1, v[118:119]
	v_or_b32_e32 v106, 0x100, v106
	v_lshl_add_u64 v[106:107], s[28:29], 0, v[106:107]
	s_and_b64 vcc, exec, s[38:39]
	s_waitcnt vmcnt(7)
	v_mov_b32_e32 v108, v228
	v_mov_b32_e32 v109, v229
	v_mov_b32_e32 v110, v230
	v_mov_b32_e32 v111, v231
	v_lshlrev_b32_e32 v112, 16, v108
	v_and_b32_e32 v113, 0xffff0000, v108
	v_lshlrev_b32_e32 v108, 16, v109
	v_and_b32_e32 v109, 0xffff0000, v109
	v_pk_fma_f32 v[104:105], v[104:105], v[40:41], v[108:109]
	v_lshlrev_b32_e32 v108, 16, v110
	v_and_b32_e32 v109, 0xffff0000, v110
	v_lshlrev_b32_e32 v110, 16, v111
	v_and_b32_e32 v111, 0xffff0000, v111
	v_pk_fma_f32 v[102:103], v[102:103], v[38:39], v[112:113]
	v_pk_fma_f32 v[100:101], v[100:101], v[48:49], v[110:111]
	v_pk_fma_f32 v[98:99], v[98:99], v[46:47], v[108:109]
	s_cbranch_vccnz .LBB0_781
	global_store_dwordx4 v[116:117], v[102:105], off offset:512
	global_store_dwordx4 v[116:117], v[98:101], off offset:528
	s_cbranch_execnz .LBB0_719

.LBB0_723:
	v_or_b32_e32 v98, 48, v166
	s_waitcnt lgkmcnt(0)
	v_ashrrev_i32_e32 v99, 31, v98
	v_lshlrev_b64 v[100:101], 10, v[98:99]
	v_lshl_add_u64 v[102:103], v[100:101], 0, v[164:165]
	v_lshl_add_u64 v[104:105], v[102:103], 1, s[28:29]
	s_and_b64 vcc, exec, s[38:39]
	s_waitcnt vmcnt(7)
	v_mov_b32_e32 v106, v232
	v_mov_b32_e32 v107, v233
	v_mov_b32_e32 v108, v234
	v_mov_b32_e32 v109, v235
	v_lshlrev_b32_e32 v100, 16, v106
	v_and_b32_e32 v101, 0xffff0000, v106
	v_lshlrev_b32_e32 v106, 16, v107
	v_and_b32_e32 v107, 0xffff0000, v107
	v_pk_fma_f32 v[96:97], v[96:97], v[52:53], v[106:107]
	v_pk_fma_f32 v[94:95], v[94:95], v[50:51], v[100:101]
	v_lshlrev_b32_e32 v100, 16, v108
	v_and_b32_e32 v101, 0xffff0000, v108
	v_lshlrev_b32_e32 v106, 16, v109
	v_and_b32_e32 v107, 0xffff0000, v109
	v_pk_fma_f32 v[92:93], v[92:93], v[56:57], v[106:107]
	v_pk_fma_f32 v[90:91], v[90:91], v[54:55], v[100:101]
	v_lshl_add_u64 v[100:101], v[102:103], 2, s[16:17]
	s_cbranch_vccnz .LBB0_782
	global_store_dwordx4 v[100:101], v[94:97], off
	global_store_dwordx4 v[100:101], v[90:93], off offset:16
	v_mov_b32_e32 v106, 0
	s_cbranch_execnz .LBB0_726

.LBB0_726:
	v_lshlrev_b64 v[90:91], 1, v[102:103]
	v_or_b32_e32 v90, 0x100, v90
	v_lshl_add_u64 v[90:91], s[28:29], 0, v[90:91]
	s_and_b64 vcc, exec, s[38:39]
	s_waitcnt vmcnt(7)
	v_mov_b32_e32 v92, v236
	v_mov_b32_e32 v93, v237
	v_mov_b32_e32 v94, v238
	v_mov_b32_e32 v95, v239
	s_mov_b64 s[98:99], 0x40000
	v_lshl_add_u64 v[182:183], v[198:199], 0, s[98:99]
	s_mov_b64 s[42:43], 0x8000
	global_load_dwordx4 v[184:187], v[182:183], off
	global_load_dwordx4 v[212:215], v[182:183], off offset:256
	v_lshl_add_u64 v[182:183], v[182:183], 0, s[42:43]
	global_load_dwordx4 v[216:219], v[182:183], off
	global_load_dwordx4 v[220:223], v[182:183], off offset:256
	v_lshl_add_u64 v[182:183], v[182:183], 0, s[42:43]
	global_load_dwordx4 v[224:227], v[182:183], off
	global_load_dwordx4 v[228:231], v[182:183], off offset:256
	v_lshl_add_u64 v[182:183], v[182:183], 0, s[42:43]
	global_load_dwordx4 v[232:235], v[182:183], off
	global_load_dwordx4 v[236:239], v[182:183], off offset:256
	v_lshlrev_b32_e32 v96, 16, v92
	v_and_b32_e32 v97, 0xffff0000, v92
	v_lshlrev_b32_e32 v92, 16, v93
	v_and_b32_e32 v93, 0xffff0000, v93
	v_pk_fma_f32 v[88:89], v[88:89], v[40:41], v[92:93]
	v_lshlrev_b32_e32 v92, 16, v94
	v_and_b32_e32 v93, 0xffff0000, v94
	v_lshlrev_b32_e32 v94, 16, v95
	v_and_b32_e32 v95, 0xffff0000, v95
	v_pk_fma_f32 v[86:87], v[86:87], v[38:39], v[96:97]
	v_pk_fma_f32 v[84:85], v[84:85], v[48:49], v[94:95]
	v_pk_fma_f32 v[82:83], v[82:83], v[46:47], v[92:93]
	s_cbranch_vccnz .LBB0_783
	global_store_dwordx4 v[100:101], v[86:89], off offset:512
	global_store_dwordx4 v[100:101], v[82:85], off offset:528
	s_cbranch_execnz .LBB0_729

.LBB0_733:
	v_add_u32_e32 v82, 0x80, v166
	s_waitcnt lgkmcnt(0)
	v_ashrrev_i32_e32 v83, 31, v82
	v_lshlrev_b64 v[84:85], 10, v[82:83]
	v_lshl_add_u64 v[86:87], v[84:85], 0, v[164:165]
	v_lshl_add_u64 v[88:89], v[86:87], 1, s[28:29]
	s_and_b64 vcc, exec, s[38:39]
	s_waitcnt vmcnt(7)
	v_mov_b32_e32 v90, v184
	v_mov_b32_e32 v91, v185
	v_mov_b32_e32 v92, v186
	v_mov_b32_e32 v93, v187
	v_lshlrev_b32_e32 v84, 16, v90
	v_and_b32_e32 v85, 0xffff0000, v90
	v_lshlrev_b32_e32 v90, 16, v91
	v_and_b32_e32 v91, 0xffff0000, v91
	v_pk_fma_f32 v[80:81], v[80:81], v[52:53], v[90:91]
	v_pk_fma_f32 v[78:79], v[78:79], v[50:51], v[84:85]
	v_lshlrev_b32_e32 v84, 16, v92
	v_and_b32_e32 v85, 0xffff0000, v92
	v_lshlrev_b32_e32 v90, 16, v93
	v_and_b32_e32 v91, 0xffff0000, v93
	v_pk_fma_f32 v[76:77], v[76:77], v[56:57], v[90:91]
	v_pk_fma_f32 v[74:75], v[74:75], v[54:55], v[84:85]
	v_lshl_add_u64 v[84:85], v[86:87], 2, s[16:17]
	s_cbranch_vccnz .LBB0_784
	global_store_dwordx4 v[84:85], v[78:81], off
	global_store_dwordx4 v[84:85], v[74:77], off offset:16
	v_mov_b32_e32 v90, 0
	s_cbranch_execnz .LBB0_736

.LBB0_736:
	v_lshlrev_b64 v[74:75], 1, v[86:87]
	v_or_b32_e32 v74, 0x100, v74
	v_lshl_add_u64 v[74:75], s[28:29], 0, v[74:75]
	s_and_b64 vcc, exec, s[38:39]
	s_waitcnt vmcnt(7)
	v_mov_b32_e32 v76, v212
	v_mov_b32_e32 v77, v213
	v_mov_b32_e32 v78, v214
	v_mov_b32_e32 v79, v215
	v_lshlrev_b32_e32 v80, 16, v76
	v_and_b32_e32 v81, 0xffff0000, v76
	v_lshlrev_b32_e32 v76, 16, v77
	v_and_b32_e32 v77, 0xffff0000, v77
	v_pk_fma_f32 v[72:73], v[72:73], v[40:41], v[76:77]
	v_lshlrev_b32_e32 v76, 16, v78
	v_and_b32_e32 v77, 0xffff0000, v78
	v_lshlrev_b32_e32 v78, 16, v79
	v_and_b32_e32 v79, 0xffff0000, v79
	v_pk_fma_f32 v[70:71], v[70:71], v[38:39], v[80:81]
	v_pk_fma_f32 v[68:69], v[68:69], v[48:49], v[78:79]
	v_pk_fma_f32 v[66:67], v[66:67], v[46:47], v[76:77]
	s_cbranch_vccnz .LBB0_785
	global_store_dwordx4 v[84:85], v[70:73], off offset:512
	global_store_dwordx4 v[84:85], v[66:69], off offset:528
	s_cbranch_execnz .LBB0_739

.LBB0_743:
	v_add_u32_e32 v66, 0x90, v166
	s_waitcnt lgkmcnt(0)
	v_ashrrev_i32_e32 v67, 31, v66
	v_lshlrev_b64 v[68:69], 10, v[66:67]
	v_lshl_add_u64 v[70:71], v[68:69], 0, v[164:165]
	v_lshl_add_u64 v[72:73], v[70:71], 1, s[28:29]
	s_and_b64 vcc, exec, s[38:39]
	s_waitcnt vmcnt(7)
	v_mov_b32_e32 v74, v216
	v_mov_b32_e32 v75, v217
	v_mov_b32_e32 v76, v218
	v_mov_b32_e32 v77, v219
	v_lshlrev_b32_e32 v68, 16, v74
	v_and_b32_e32 v69, 0xffff0000, v74
	v_lshlrev_b32_e32 v74, 16, v75
	v_and_b32_e32 v75, 0xffff0000, v75
	v_pk_fma_f32 v[64:65], v[64:65], v[52:53], v[74:75]
	v_pk_fma_f32 v[62:63], v[62:63], v[50:51], v[68:69]
	v_lshlrev_b32_e32 v68, 16, v76
	v_and_b32_e32 v69, 0xffff0000, v76
	v_lshlrev_b32_e32 v74, 16, v77
	v_and_b32_e32 v75, 0xffff0000, v77
	v_pk_fma_f32 v[60:61], v[60:61], v[56:57], v[74:75]
	v_pk_fma_f32 v[58:59], v[58:59], v[54:55], v[68:69]
	v_lshl_add_u64 v[68:69], v[70:71], 2, s[16:17]
	s_cbranch_vccnz .LBB0_786
	global_store_dwordx4 v[68:69], v[62:65], off
	global_store_dwordx4 v[68:69], v[58:61], off offset:16
	v_mov_b32_e32 v74, 0
	s_cbranch_execnz .LBB0_746

.LBB0_746:
	v_lshlrev_b64 v[58:59], 1, v[70:71]
	v_or_b32_e32 v58, 0x100, v58
	v_lshl_add_u64 v[58:59], s[28:29], 0, v[58:59]
	s_and_b64 vcc, exec, s[38:39]
	s_waitcnt vmcnt(7)
	v_mov_b32_e32 v60, v220
	v_mov_b32_e32 v61, v221
	v_mov_b32_e32 v62, v222
	v_mov_b32_e32 v63, v223
	v_lshlrev_b32_e32 v64, 16, v60
	v_and_b32_e32 v65, 0xffff0000, v60
	v_lshlrev_b32_e32 v60, 16, v61
	v_and_b32_e32 v61, 0xffff0000, v61
	v_pk_fma_f32 v[44:45], v[44:45], v[40:41], v[60:61]
	v_lshlrev_b32_e32 v60, 16, v62
	v_and_b32_e32 v61, 0xffff0000, v62
	v_lshlrev_b32_e32 v62, 16, v63
	v_and_b32_e32 v63, 0xffff0000, v63
	v_pk_fma_f32 v[42:43], v[42:43], v[38:39], v[64:65]
	v_pk_fma_f32 v[36:37], v[36:37], v[48:49], v[62:63]
	v_pk_fma_f32 v[34:35], v[34:35], v[46:47], v[60:61]
	s_cbranch_vccnz .LBB0_787
	global_store_dwordx4 v[68:69], v[42:45], off offset:512
	global_store_dwordx4 v[68:69], v[34:37], off offset:528
	s_cbranch_execnz .LBB0_749

.LBB0_753:
	v_add_u32_e32 v34, 0xa0, v166
	s_waitcnt lgkmcnt(0)
	v_ashrrev_i32_e32 v35, 31, v34
	v_lshlrev_b64 v[36:37], 10, v[34:35]
	v_lshl_add_u64 v[42:43], v[36:37], 0, v[164:165]
	v_lshl_add_u64 v[44:45], v[42:43], 1, s[28:29]
	s_and_b64 vcc, exec, s[38:39]
	s_waitcnt vmcnt(7)
	v_mov_b32_e32 v58, v224
	v_mov_b32_e32 v59, v225
	v_mov_b32_e32 v60, v226
	v_mov_b32_e32 v61, v227
	v_lshlrev_b32_e32 v36, 16, v58
	v_and_b32_e32 v37, 0xffff0000, v58
	v_lshlrev_b32_e32 v58, 16, v59
	v_and_b32_e32 v59, 0xffff0000, v59
	v_pk_fma_f32 v[32:33], v[32:33], v[52:53], v[58:59]
	v_pk_fma_f32 v[30:31], v[30:31], v[50:51], v[36:37]
	v_lshlrev_b32_e32 v36, 16, v60
	v_and_b32_e32 v37, 0xffff0000, v60
	v_lshlrev_b32_e32 v58, 16, v61
	v_and_b32_e32 v59, 0xffff0000, v61
	v_pk_fma_f32 v[28:29], v[28:29], v[56:57], v[58:59]
	v_pk_fma_f32 v[26:27], v[26:27], v[54:55], v[36:37]
	v_lshl_add_u64 v[36:37], v[42:43], 2, s[16:17]
	s_cbranch_vccnz .LBB0_788
	global_store_dwordx4 v[36:37], v[30:33], off
	global_store_dwordx4 v[36:37], v[26:29], off offset:16
	v_mov_b32_e32 v58, 0
	s_cbranch_execnz .LBB0_756

.LBB0_756:
	v_lshlrev_b64 v[26:27], 1, v[42:43]
	v_or_b32_e32 v26, 0x100, v26
	v_lshl_add_u64 v[26:27], s[28:29], 0, v[26:27]
	s_and_b64 vcc, exec, s[38:39]
	s_waitcnt vmcnt(7)
	v_mov_b32_e32 v28, v228
	v_mov_b32_e32 v29, v229
	v_mov_b32_e32 v30, v230
	v_mov_b32_e32 v31, v231
	v_lshlrev_b32_e32 v32, 16, v28
	v_and_b32_e32 v33, 0xffff0000, v28
	v_lshlrev_b32_e32 v28, 16, v29
	v_and_b32_e32 v29, 0xffff0000, v29
	v_pk_fma_f32 v[24:25], v[24:25], v[40:41], v[28:29]
	v_lshlrev_b32_e32 v28, 16, v30
	v_and_b32_e32 v29, 0xffff0000, v30
	v_lshlrev_b32_e32 v30, 16, v31
	v_and_b32_e32 v31, 0xffff0000, v31
	v_pk_fma_f32 v[22:23], v[22:23], v[38:39], v[32:33]
	v_pk_fma_f32 v[20:21], v[20:21], v[48:49], v[30:31]
	v_pk_fma_f32 v[18:19], v[18:19], v[46:47], v[28:29]
	s_cbranch_vccnz .LBB0_789
	global_store_dwordx4 v[36:37], v[22:25], off offset:512
	global_store_dwordx4 v[36:37], v[18:21], off offset:528
	s_cbranch_execnz .LBB0_759

.LBB0_763:
	v_add_u32_e32 v18, 0xb0, v166
	s_waitcnt lgkmcnt(0)
	v_ashrrev_i32_e32 v19, 31, v18
	v_lshlrev_b64 v[20:21], 10, v[18:19]
	v_lshl_add_u64 v[22:23], v[20:21], 0, v[164:165]
	v_lshl_add_u64 v[24:25], v[22:23], 1, s[28:29]
	s_and_b64 vcc, exec, s[38:39]
	s_waitcnt vmcnt(7)
	v_mov_b32_e32 v26, v232
	v_mov_b32_e32 v27, v233
	v_mov_b32_e32 v28, v234
	v_mov_b32_e32 v29, v235
	v_lshlrev_b32_e32 v20, 16, v26
	v_and_b32_e32 v21, 0xffff0000, v26
	v_lshlrev_b32_e32 v26, 16, v27
	v_and_b32_e32 v27, 0xffff0000, v27
	v_pk_fma_f32 v[16:17], v[16:17], v[52:53], v[26:27]
	v_pk_fma_f32 v[14:15], v[14:15], v[50:51], v[20:21]
	v_lshlrev_b32_e32 v20, 16, v28
	v_and_b32_e32 v21, 0xffff0000, v28
	v_lshlrev_b32_e32 v26, 16, v29
	v_and_b32_e32 v27, 0xffff0000, v29
	v_pk_fma_f32 v[12:13], v[12:13], v[56:57], v[26:27]
	v_pk_fma_f32 v[10:11], v[10:11], v[54:55], v[20:21]
	v_lshl_add_u64 v[20:21], v[22:23], 2, s[16:17]
	s_cbranch_vccnz .LBB0_790
	global_store_dwordx4 v[20:21], v[14:17], off
	global_store_dwordx4 v[20:21], v[10:13], off offset:16
	v_mov_b32_e32 v26, 0
	s_cbranch_execnz .LBB0_766

.LBB0_766:
	v_lshlrev_b64 v[10:11], 1, v[22:23]
	v_or_b32_e32 v10, 0x100, v10
	v_lshl_add_u64 v[10:11], s[28:29], 0, v[10:11]
	s_and_b64 vcc, exec, s[38:39]
	s_waitcnt vmcnt(7)
	v_mov_b32_e32 v12, v236
	v_mov_b32_e32 v13, v237
	v_mov_b32_e32 v14, v238
	v_mov_b32_e32 v15, v239
	v_lshlrev_b32_e32 v16, 16, v12
	v_and_b32_e32 v17, 0xffff0000, v12
	v_lshlrev_b32_e32 v12, 16, v13
	v_and_b32_e32 v13, 0xffff0000, v13
	v_pk_fma_f32 v[8:9], v[8:9], v[40:41], v[12:13]
	v_lshlrev_b32_e32 v12, 16, v14
	v_and_b32_e32 v13, 0xffff0000, v14
	v_lshlrev_b32_e32 v14, 16, v15
	v_and_b32_e32 v15, 0xffff0000, v15
	v_pk_fma_f32 v[6:7], v[6:7], v[38:39], v[16:17]
	v_pk_fma_f32 v[4:5], v[4:5], v[48:49], v[14:15]
	v_pk_fma_f32 v[2:3], v[2:3], v[46:47], v[12:13]
	s_cbranch_vccnz .LBB0_791
	global_store_dwordx4 v[20:21], v[6:9], off offset:512
	global_store_dwordx4 v[20:21], v[2:5], off offset:528
	s_cbranch_execnz .LBB0_769
